# attention item epilogue: bf16 row stores widened from 16x dwordx2 to 8x dwordx4 per lane by v_permlane32_swap pairing (guide 7.3)
# speedup vs baseline: 1.0020x; 1.0020x over previous
.Lq_pref_skip2:
	s_or_b64 exec, exec, s[24:25]
	v_lshl_add_u64 v[2:3], v[224:225], 2, v[216:217]
	v_mul_f32_e32 v84, v142, v0
	v_mul_f32_e32 v85, v12, v26
	v_mul_f32_e32 v86, v13, v26
	v_mul_f32_e32 v87, v14, v26
	v_mul_f32_e32 v85, v143, v85
	v_mul_f32_e32 v86, v144, v86
	v_mul_f32_e32 v87, v145, v87
	v_mul_f32_e32 v88, v15, v26
	v_mul_f32_e32 v89, v64, v26
	v_mul_f32_e32 v90, v65, v26
	v_mul_f32_e32 v91, v66, v26
	v_mul_f32_e32 v88, v88, v146
	v_mul_f32_e32 v89, v89, v147
	v_mul_f32_e32 v90, v90, v148
	v_mul_f32_e32 v91, v91, v149
	v_cvt_pk_bf16_f32 v92, v84, v85
	v_cvt_pk_bf16_f32 v93, v86, v87
	v_cvt_pk_bf16_f32 v94, v88, v89
	v_cvt_pk_bf16_f32 v95, v90, v91
	s_nop 1
	v_permlane32_swap_b32_e32 v92, v94
	v_permlane32_swap_b32_e32 v93, v95
	global_store_dwordx4 v[2:3], v[92:95], off
	v_mul_f32_e32 v84, v67, v26
	v_mul_f32_e32 v85, v68, v26
	v_mul_f32_e32 v86, v69, v26
	v_mul_f32_e32 v87, v70, v26
	v_mul_f32_e32 v84, v84, v150
	v_mul_f32_e32 v85, v85, v151
	v_mul_f32_e32 v86, v86, v152
	v_mul_f32_e32 v87, v87, v153
	v_mul_f32_e32 v88, v71, v26
	v_mul_f32_e32 v89, v72, v26
	v_mul_f32_e32 v90, v73, v26
	v_mul_f32_e32 v91, v74, v26
	v_mul_f32_e32 v88, v88, v154
	v_mul_f32_e32 v89, v89, v155
	v_mul_f32_e32 v90, v90, v156
	v_mul_f32_e32 v91, v91, v157
	v_cvt_pk_bf16_f32 v92, v84, v85
	v_cvt_pk_bf16_f32 v93, v86, v87
	v_cvt_pk_bf16_f32 v94, v88, v89
	v_cvt_pk_bf16_f32 v95, v90, v91
	s_nop 1
	v_permlane32_swap_b32_e32 v92, v94
	v_permlane32_swap_b32_e32 v93, v95
	global_store_dwordx4 v[2:3], v[92:95], off offset:32
	v_mul_f32_e32 v84, v48, v26
	v_mul_f32_e32 v85, v49, v26
	v_mul_f32_e32 v86, v50, v26
	v_mul_f32_e32 v87, v51, v26
	v_mul_f32_e32 v84, v84, v158
	v_mul_f32_e32 v85, v85, v159
	v_mul_f32_e32 v86, v86, v160
	v_mul_f32_e32 v87, v87, v161
	v_mul_f32_e32 v88, v75, v26
	v_mul_f32_e32 v89, v52, v26
	v_mul_f32_e32 v90, v76, v26
	v_mul_f32_e32 v91, v55, v26
	v_mul_f32_e32 v88, v88, v162
	v_mul_f32_e32 v89, v89, v163
	v_mul_f32_e32 v90, v90, v164
	v_mul_f32_e32 v91, v91, v165
	v_cvt_pk_bf16_f32 v92, v84, v85
	v_cvt_pk_bf16_f32 v93, v86, v87
	v_cvt_pk_bf16_f32 v94, v88, v89
	v_cvt_pk_bf16_f32 v95, v90, v91
	s_nop 1
	v_permlane32_swap_b32_e32 v92, v94
	v_permlane32_swap_b32_e32 v93, v95
	global_store_dwordx4 v[2:3], v[92:95], off offset:64
	v_mul_f32_e32 v84, v54, v26
	v_mul_f32_e32 v85, v53, v26
	v_mul_f32_e32 v86, v57, v26
	v_mul_f32_e32 v87, v56, v26
	v_mul_f32_e32 v84, v84, v166
	v_mul_f32_e32 v85, v85, v167
	v_mul_f32_e32 v86, v86, v168
	v_mul_f32_e32 v87, v87, v169
	v_mul_f32_e32 v88, v59, v26
	v_mul_f32_e32 v89, v58, v26
	v_mul_f32_e32 v90, v62, v26
	v_mul_f32_e32 v91, v60, v26
	v_mul_f32_e32 v88, v88, v170
	v_mul_f32_e32 v89, v89, v171
	v_mul_f32_e32 v90, v90, v172
	v_mul_f32_e32 v91, v91, v173
	v_cvt_pk_bf16_f32 v92, v84, v85
	v_cvt_pk_bf16_f32 v93, v86, v87
	v_cvt_pk_bf16_f32 v94, v88, v89
	v_cvt_pk_bf16_f32 v95, v90, v91
	s_nop 1
	v_permlane32_swap_b32_e32 v92, v94
	v_permlane32_swap_b32_e32 v93, v95
	global_store_dwordx4 v[2:3], v[92:95], off offset:96
	v_mul_f32_e32 v84, v61, v26
	v_mul_f32_e32 v85, v32, v26
	v_mul_f32_e32 v86, v34, v26
	v_mul_f32_e32 v87, v33, v26
	v_mul_f32_e32 v84, v84, v174
	v_mul_f32_e32 v85, v85, v175
	v_mul_f32_e32 v86, v86, v176
	v_mul_f32_e32 v87, v87, v177
	v_mul_f32_e32 v88, v36, v26
	v_mul_f32_e32 v89, v35, v26
	v_mul_f32_e32 v90, v63, v26
	v_mul_f32_e32 v91, v39, v26
	v_mul_f32_e32 v88, v88, v178
	v_mul_f32_e32 v89, v89, v179
	v_mul_f32_e32 v90, v90, v180
	v_mul_f32_e32 v91, v91, v181
	v_cvt_pk_bf16_f32 v92, v84, v85
	v_cvt_pk_bf16_f32 v93, v86, v87
	v_cvt_pk_bf16_f32 v94, v88, v89
	v_cvt_pk_bf16_f32 v95, v90, v91
	s_nop 1
	v_permlane32_swap_b32_e32 v92, v94
	v_permlane32_swap_b32_e32 v93, v95
	global_store_dwordx4 v[2:3], v[92:95], off offset:128
	v_mul_f32_e32 v84, v38, v26
	v_mul_f32_e32 v85, v37, v26
	v_mul_f32_e32 v86, v41, v26
	v_mul_f32_e32 v87, v40, v26
	v_mul_f32_e32 v84, v84, v182
	v_mul_f32_e32 v85, v85, v183
	v_mul_f32_e32 v86, v86, v184
	v_mul_f32_e32 v87, v87, v185
	v_mul_f32_e32 v88, v43, v26
	v_mul_f32_e32 v89, v42, v26
	v_mul_f32_e32 v90, v46, v26
	v_mul_f32_e32 v91, v45, v26
	v_mul_f32_e32 v88, v88, v186
	v_mul_f32_e32 v89, v89, v187
	v_mul_f32_e32 v90, v90, v188
	v_mul_f32_e32 v91, v91, v189
	v_cvt_pk_bf16_f32 v92, v84, v85
	v_cvt_pk_bf16_f32 v93, v86, v87
	v_cvt_pk_bf16_f32 v94, v88, v89
	v_cvt_pk_bf16_f32 v95, v90, v91
	s_nop 1
	v_permlane32_swap_b32_e32 v92, v94
	v_permlane32_swap_b32_e32 v93, v95
	global_store_dwordx4 v[2:3], v[92:95], off offset:160
	v_mul_f32_e32 v84, v44, v26
	v_mul_f32_e32 v85, v16, v26
	v_mul_f32_e32 v86, v18, v26
	v_mul_f32_e32 v87, v17, v26
	v_mul_f32_e32 v84, v84, v190
	v_mul_f32_e32 v85, v85, v191
	v_mul_f32_e32 v86, v86, v192
	v_mul_f32_e32 v87, v87, v193
	v_mul_f32_e32 v88, v20, v26
	v_mul_f32_e32 v89, v19, v26
	v_mul_f32_e32 v90, v47, v26
	v_mul_f32_e32 v91, v23, v26
	v_mul_f32_e32 v88, v88, v194
	v_mul_f32_e32 v89, v89, v195
	v_mul_f32_e32 v90, v90, v196
	v_mul_f32_e32 v91, v91, v197
	v_cvt_pk_bf16_f32 v92, v84, v85
	v_cvt_pk_bf16_f32 v93, v86, v87
	v_cvt_pk_bf16_f32 v94, v88, v89
	v_cvt_pk_bf16_f32 v95, v90, v91
	s_nop 1
	v_permlane32_swap_b32_e32 v92, v94
	v_permlane32_swap_b32_e32 v93, v95
	global_store_dwordx4 v[2:3], v[92:95], off offset:192
	v_mul_f32_e32 v84, v22, v26
	v_mul_f32_e32 v85, v21, v26
	v_mul_f32_e32 v86, v25, v26
	v_mul_f32_e32 v87, v24, v26
	v_mul_f32_e32 v84, v84, v198
	v_mul_f32_e32 v85, v85, v199
	v_mul_f32_e32 v86, v86, v200
	v_mul_f32_e32 v87, v87, v201
	v_mul_f32_e32 v88, v6, v26
	v_mul_f32_e32 v89, v7, v26
	v_mul_f32_e32 v90, v8, v26
	v_mul_f32_e32 v91, v9, v26
	v_mul_f32_e32 v88, v88, v202
	v_mul_f32_e32 v89, v89, v203
	v_mul_f32_e32 v90, v90, v204
	v_mul_f32_e32 v91, v91, v205
	v_cvt_pk_bf16_f32 v92, v84, v85
	v_cvt_pk_bf16_f32 v93, v86, v87
	v_cvt_pk_bf16_f32 v94, v88, v89
	v_cvt_pk_bf16_f32 v95, v90, v91
	s_nop 1
	v_permlane32_swap_b32_e32 v92, v94
	v_permlane32_swap_b32_e32 v93, v95
	global_store_dwordx4 v[2:3], v[92:95], off offset:224
	s_branch .LBB0_494
